# SwiGLU epilogues of FFN1-up and FFN2-up hand-written (packed f32) with the row sum-of-squares prefetched one unit ahead into spare VGPRs
# speedup vs baseline: 1.0038x; 1.0038x over previous
;     __device__ __forceinline__ void a_ready(const Unit&) const { wait_cnt(w_ready, w_need); }
; #define PG8_STAGE(bufoff, gbase, voff) do { _Pragma("unroll") for (int _i = 0; _i < 2; ++_i) \
;         asm volatile("s_mov_b32 m0, %0\n\ts_nop 0\n\tglobal_load_lds_dwordx4 %1, %2" :: "s"(ldsb + (unsigned)(bufoff) + ldsw + (unsigned)(_i * 8192)), "v"((voff)[_i]), "s"((const char*)(gbase)) : "memory", "m0"); } while (0)
; #define PG8_WAIT_V(n) asm volatile("s_waitcnt vmcnt(" #n ")" ::: "memory")
; #define PG8_BAR __builtin_amdgcn_s_barrier()
; template <class Epi, class Sched>
; __device__ __forceinline__ void gemm_phase(LAS unsigned char* lds, const Gemm g, const Sched& S, const Epi& E) {
;     ...
;     const char* cA = (const char*)g.A + (size_t)cur.pm * tstepA + (size_t)cur.kt0 * kstep;
;     const char* cB = (const char*)g.Bt + (size_t)cur.pn * tstepB + (size_t)cur.kt0 * kstep;
;     S.a_ready(cur);
;     PG8_STAGE(PG8_SB(0, 0), cB, voffB); PG8_STAGE(PG8_SB(0, 1), cB + hstepB, voffB); PG8_STAGE(PG8_SA(0, 0), cA, voffA); PG8_STAGE(PG8_SA(0, 1), cA + hstepA, voffA);
;     if (wr == 1) PG8_BAR;
;     PG8_WAIT_V(2); PG8_BAR;
;     PG8_STAGE(PG8_SB(1, 0), cB + kstep, voffB); PG8_STAGE(PG8_SA(1, 0), cA + kstep, voffA); PG8_STAGE(PG8_SB(1, 1), cB + hstepB + kstep, voffB);
;     PG8_WAIT_V(6); PG8_BAR;
;     __device__ __forceinline__ void operator()(const Acc& acc, const Unit& u, int wr, int wc, int fr, int fq) const {
;         int row0 = u.pm * BM + wr * 64 + fr, colh = u.pn * 128 + wc * 32 + 8 * fq; asm volatile("" : "+v"(row0), "+v"(colh));
;         float sq[2][4];
; #pragma unroll
;         for (int ai = 0; ai < 2; ++ai)
; #pragma unroll
;             for (int m = 0; m < 4; ++m) sq[ai][m] = ssq[row0 + ai * HALF + m * 16];
.LBB0_158:
	v_and_b32_e32 v2, 24, v2
	v_and_b32_e32 v3, 15, v0
	v_lshlrev_b32_e32 v4, 1, v2
	v_lshlrev_b32_e32 v5, 2, v0
	v_lshl_or_b32 v136, s10, 6, v3
	v_lshl_or_b32 v3, v3, 6, v4
	s_lshl_b32 s7, s10, 13
	v_and_b32_e32 v5, 32, v5
	v_bitop3_b32 v3, v3, s7, v5 bitop3:0xde
	s_lshl_b32 s7, s11, 5
	s_and_b32 s12, s7, 0x60
	v_lshlrev_b32_e32 v6, 6, v0
	s_movk_i32 s7, 0x3c0
	v_and_or_b32 v4, v6, s7, v4
	s_lshl_b32 s7, s12, 7
	s_add_i32 s64, s56, 0x18000
	s_add_u32 s10, s52, 0x80
	s_waitcnt vmcnt(2)
	s_barrier
	s_addc_u32 s11, s53, 0
	s_mov_b32 m0, s64
	s_nop 0
	global_load_lds_dwordx4 v133, s[10:11]
	s_add_i32 s65, s56, 0x1a000
	s_add_i32 s66, s56, 0x8000
	s_mov_b32 m0, s65
	s_nop 0
	global_load_lds_dwordx4 v135, s[10:11]
	s_add_u32 s10, s44, 0x80
	s_addc_u32 s11, s45, 0
	s_mov_b32 m0, s66
	s_nop 0
	global_load_lds_dwordx4 v132, s[10:11]
	s_add_i32 s67, s56, 0xa000
	s_add_i32 s68, s56, 0x1c000
	s_mov_b32 m0, s67
	s_nop 0
	global_load_lds_dwordx4 v134, s[10:11]
	s_add_u32 s10, s52, 0x80080
	s_addc_u32 s11, s53, 0
	s_mov_b32 m0, s68
	s_nop 0
	global_load_lds_dwordx4 v133, s[10:11]
	s_add_i32 s69, s56, 0x1e000
	s_mov_b32 m0, s69
	s_nop 0
	global_load_lds_dwordx4 v135, s[10:11]
	v_bitop3_b32 v4, s7, v4, v5 bitop3:0xf6
	s_waitcnt vmcnt(6)
	s_add_i32 s70, s56, 0xc000
	s_cmpk_lt_u32 s9, 0x100
	v_or_b32_e32 v137, s12, v2
	v_add_u32_e32 v2, 0, v4
	s_sext_i32_i16 s7, s8
	s_cselect_b64 s[8:9], -1, 0
	s_add_i32 s71, s56, 0xe000
	v_mov_b64_e32 v[130:131], 0x57f
	v_add_u32_e32 v138, 0x10000, v2
	v_add_u32_e32 v139, 0x14000, v2
	v_add_u32_e32 v140, 0, v3
	v_add_u32_e32 v141, 0x18000, v2
	v_add_u32_e32 v142, 0x1c000, v2
	v_mov_b32_e32 v143, 0x358637bd
	s_mov_b32 s72, 0x800000
	s_movk_i32 s73, 0x2c00
	s_barrier
	v_lshl_add_u32 v224, s6, 8, v136
	v_lshlrev_b32_e32 v224, 2, v224
	global_load_dword v216, v224, s[88:89]
	global_load_dword v217, v224, s[88:89] offset:64
	global_load_dword v218, v224, s[88:89] offset:128
	global_load_dword v219, v224, s[88:89] offset:192
	global_load_dword v220, v224, s[88:89] offset:512
	global_load_dword v221, v224, s[88:89] offset:576
	global_load_dword v222, v224, s[88:89] offset:640
	global_load_dword v223, v224, s[88:89] offset:704
	s_branch .LBB0_161

; __device__ __forceinline__ float fsilu(float x) { return x * fsigmoid(x); }
; __device__ __forceinline__ u32x4 pack8(const f32x4 a, const f32x4 b) { u32x4 w; w.x = cvt_pk_bf16(a[0], a[1]); w.y = cvt_pk_bf16(a[2], a[3]); w.z = cvt_pk_bf16(b[0], b[1]); w.w = cvt_pk_bf16(b[2], b[3]); return w; }
;     __device__ __forceinline__ void operator()(const Acc& acc, const Unit& u, int wr, int wc, int fr, int fq) const {
;         int row0 = u.pm * BM + wr * 64 + fr, colh = u.pn * 128 + wc * 32 + 8 * fq; asm volatile("" : "+v"(row0), "+v"(colh));
;         float sq[2][4];
; #pragma unroll
;         for (int ai = 0; ai < 2; ++ai)
; #pragma unroll
;             for (int m = 0; m < 4; ++m) sq[ai][m] = ssq[row0 + ai * HALF + m * 16];
;         asm volatile("" ::: "memory");
; #pragma unroll
;         for (int ai = 0; ai < 2; ++ai)
; #pragma unroll
;             for (int m = 0; m < 4; ++m) {
;                 const int row = row0 + ai * HALF + m * 16;
;                 const float r = rsqrtf(sq[ai][m] * (1.0f / D) + EPS);
;                 f32x4 h0, h1;
; #pragma unroll
;                 for (int j = 0; j < 4; ++j) { h0[j] = fsilu(acc[ai][0][m][0][j] * r) * (acc[ai][1][m][0][j] * r); h1[j] = fsilu(acc[ai][0][m][1][j] * r) * (acc[ai][1][m][1][j] * r); }
;                 *(u32x4*)(O + (size_t)row * FF + colh) = pack8(h0, h1);
;             }
.LBB0_172:
	v_lshl_add_u32 v144, s6, 8, v136
	v_lshl_or_b32 v145, s7, 7, v137
	v_lshlrev_b32_e32 v146, 2, v144
	v_readlane_b32 s6, v254, 40
	v_readlane_b32 s7, v254, 41
	v_mul_u32_u24_e32 v147, 0x2c00, v144
	v_lshl_add_u32 v147, v145, 1, v147
	v_pk_mul_f32 v[126:127], v[122:123], v[126:127]
	v_pk_mul_f32 v[128:129], v[124:125], v[128:129]
	v_pk_mul_f32 v[118:119], v[114:115], v[118:119]
	v_pk_mul_f32 v[120:121], v[116:117], v[120:121]
	v_pk_mul_f32 v[94:95], v[110:111], v[94:95]
	v_pk_mul_f32 v[96:97], v[112:113], v[96:97]
	v_pk_mul_f32 v[90:91], v[106:107], v[90:91]
	v_pk_mul_f32 v[92:93], v[108:109], v[92:93]
	v_pk_mul_f32 v[54:55], v[78:79], v[54:55]
	v_pk_mul_f32 v[56:57], v[80:81], v[56:57]
	v_pk_mul_f32 v[50:51], v[66:67], v[50:51]
	v_pk_mul_f32 v[52:53], v[68:69], v[52:53]
	v_pk_mul_f32 v[22:23], v[38:39], v[22:23]
	v_pk_mul_f32 v[24:25], v[40:41], v[24:25]
	v_pk_mul_f32 v[18:19], v[26:27], v[18:19]
	v_pk_mul_f32 v[20:21], v[28:29], v[20:21]
	v_pk_mul_f32 v[102:103], v[86:87], v[102:103]
	v_pk_mul_f32 v[104:105], v[88:89], v[104:105]
	v_pk_mul_f32 v[98:99], v[82:83], v[98:99]
	v_pk_mul_f32 v[100:101], v[84:85], v[100:101]
	v_pk_mul_f32 v[74:75], v[62:63], v[74:75]
	v_pk_mul_f32 v[76:77], v[64:65], v[76:77]
	v_pk_mul_f32 v[70:71], v[58:59], v[70:71]
	v_pk_mul_f32 v[72:73], v[60:61], v[72:73]
	v_pk_mul_f32 v[46:47], v[34:35], v[46:47]
	v_pk_mul_f32 v[48:49], v[36:37], v[48:49]
	v_pk_mul_f32 v[42:43], v[30:31], v[42:43]
	v_pk_mul_f32 v[44:45], v[32:33], v[44:45]
	v_pk_mul_f32 v[14:15], v[6:7], v[14:15]
	v_pk_mul_f32 v[16:17], v[8:9], v[16:17]
	v_pk_mul_f32 v[10:11], v[2:3], v[10:11]
	v_pk_mul_f32 v[12:13], v[4:5], v[12:13]
	v_fmamk_f32 v150, v216, 0x3a000000, v143
	v_fmamk_f32 v152, v217, 0x3a000000, v143
	v_fmamk_f32 v154, v218, 0x3a000000, v143
	v_fmamk_f32 v156, v219, 0x3a000000, v143
	v_fmamk_f32 v158, v220, 0x3a000000, v143
	v_fmamk_f32 v160, v221, 0x3a000000, v143
	v_fmamk_f32 v162, v222, 0x3a000000, v143
	v_fmamk_f32 v164, v223, 0x3a000000, v143
	v_rsq_f32_e32 v166, v150
	v_rsq_f32_e32 v168, v152
	v_rsq_f32_e32 v170, v154
	v_rsq_f32_e32 v172, v156
	v_rsq_f32_e32 v174, v158
	v_rsq_f32_e32 v176, v160
	v_rsq_f32_e32 v178, v162
	v_rsq_f32_e32 v184, v164
	v_mul_f32_e32 v166, 0xbfb8aa3b, v166
	v_mul_f32_e32 v168, 0xbfb8aa3b, v168
	v_mul_f32_e32 v170, 0xbfb8aa3b, v170
	v_mul_f32_e32 v172, 0xbfb8aa3b, v172
	v_mul_f32_e32 v174, 0xbfb8aa3b, v174
	v_mul_f32_e32 v176, 0xbfb8aa3b, v176
	v_mul_f32_e32 v178, 0xbfb8aa3b, v178
	v_mul_f32_e32 v184, 0xbfb8aa3b, v184
	v_pk_mul_f32 v[186:187], v[122:123], v[166:167] op_sel_hi:[1,0]
	v_pk_mul_f32 v[188:189], v[124:125], v[166:167] op_sel_hi:[1,0]
	v_pk_mul_f32 v[190:191], v[114:115], v[166:167] op_sel_hi:[1,0]
	v_pk_mul_f32 v[192:193], v[116:117], v[166:167] op_sel_hi:[1,0]
	v_exp_f32_e32 v186, v186
	v_exp_f32_e32 v187, v187
	v_exp_f32_e32 v188, v188
	v_exp_f32_e32 v189, v189
	v_exp_f32_e32 v190, v190
	v_exp_f32_e32 v191, v191
	v_exp_f32_e32 v192, v192
	v_exp_f32_e32 v193, v193
	v_pk_fma_f32 v[186:187], v[186:187], v[150:151], v[150:151] op_sel_hi:[1,0,0]
	v_pk_fma_f32 v[188:189], v[188:189], v[150:151], v[150:151] op_sel_hi:[1,0,0]
	v_pk_fma_f32 v[190:191], v[190:191], v[150:151], v[150:151] op_sel_hi:[1,0,0]
	v_pk_fma_f32 v[192:193], v[192:193], v[150:151], v[150:151] op_sel_hi:[1,0,0]
	v_rcp_f32_e32 v186, v186
	v_rcp_f32_e32 v187, v187
	v_rcp_f32_e32 v188, v188
	v_rcp_f32_e32 v189, v189
	v_rcp_f32_e32 v190, v190
	v_rcp_f32_e32 v191, v191
	v_rcp_f32_e32 v192, v192
	v_rcp_f32_e32 v193, v193
	v_pk_mul_f32 v[126:127], v[126:127], v[186:187]
	v_pk_mul_f32 v[128:129], v[128:129], v[188:189]
	v_pk_mul_f32 v[118:119], v[118:119], v[190:191]
	v_pk_mul_f32 v[120:121], v[120:121], v[192:193]
	v_cvt_pk_bf16_f32 v122, v126, v127
	v_cvt_pk_bf16_f32 v123, v128, v129
	v_cvt_pk_bf16_f32 v124, v118, v119
	v_cvt_pk_bf16_f32 v125, v120, v121
	global_store_dwordx4 v147, v[122:125], s[6:7] sc1
	v_pk_mul_f32 v[186:187], v[110:111], v[168:169] op_sel_hi:[1,0]
	v_pk_mul_f32 v[188:189], v[112:113], v[168:169] op_sel_hi:[1,0]
	v_pk_mul_f32 v[190:191], v[106:107], v[168:169] op_sel_hi:[1,0]
	v_pk_mul_f32 v[192:193], v[108:109], v[168:169] op_sel_hi:[1,0]
	v_exp_f32_e32 v186, v186
	v_exp_f32_e32 v187, v187
	v_exp_f32_e32 v188, v188
	v_exp_f32_e32 v189, v189
	v_exp_f32_e32 v190, v190
	v_exp_f32_e32 v191, v191
	v_exp_f32_e32 v192, v192
	v_exp_f32_e32 v193, v193
	v_pk_fma_f32 v[186:187], v[186:187], v[152:153], v[152:153] op_sel_hi:[1,0,0]
	v_pk_fma_f32 v[188:189], v[188:189], v[152:153], v[152:153] op_sel_hi:[1,0,0]
	v_pk_fma_f32 v[190:191], v[190:191], v[152:153], v[152:153] op_sel_hi:[1,0,0]
	v_pk_fma_f32 v[192:193], v[192:193], v[152:153], v[152:153] op_sel_hi:[1,0,0]
	v_rcp_f32_e32 v186, v186
	v_rcp_f32_e32 v187, v187
	v_rcp_f32_e32 v188, v188
	v_rcp_f32_e32 v189, v189
	v_rcp_f32_e32 v190, v190
	v_rcp_f32_e32 v191, v191
	v_rcp_f32_e32 v192, v192
	v_rcp_f32_e32 v193, v193
	v_pk_mul_f32 v[94:95], v[94:95], v[186:187]
	v_pk_mul_f32 v[96:97], v[96:97], v[188:189]
	v_pk_mul_f32 v[90:91], v[90:91], v[190:191]
	v_pk_mul_f32 v[92:93], v[92:93], v[192:193]
	v_cvt_pk_bf16_f32 v110, v94, v95
	v_cvt_pk_bf16_f32 v111, v96, v97
	v_cvt_pk_bf16_f32 v112, v90, v91
	v_cvt_pk_bf16_f32 v113, v92, v93
	v_add_u32_e32 v148, 0x2c000, v147
	global_store_dwordx4 v148, v[110:113], s[6:7] sc1
	v_pk_mul_f32 v[186:187], v[78:79], v[170:171] op_sel_hi:[1,0]
	v_pk_mul_f32 v[188:189], v[80:81], v[170:171] op_sel_hi:[1,0]
	v_pk_mul_f32 v[190:191], v[66:67], v[170:171] op_sel_hi:[1,0]
	v_pk_mul_f32 v[192:193], v[68:69], v[170:171] op_sel_hi:[1,0]
	v_exp_f32_e32 v186, v186
	v_exp_f32_e32 v187, v187
	v_exp_f32_e32 v188, v188
	v_exp_f32_e32 v189, v189
; __device__ __forceinline__ float fsilu(float x) { return x * fsigmoid(x); }
; __device__ __forceinline__ u32x4 pack8(const f32x4 a, const f32x4 b) { u32x4 w; w.x = cvt_pk_bf16(a[0], a[1]); w.y = cvt_pk_bf16(a[2], a[3]); w.z = cvt_pk_bf16(b[0], b[1]); w.w = cvt_pk_bf16(b[2], b[3]); return w; }
;     __device__ __forceinline__ void operator()(const Acc& acc, const Unit& u, int wr, int wc, int fr, int fq) const {
;     ...
;                 const float r = rsqrtf(sq[ai][m] * (1.0f / D) + EPS);
;                 f32x4 h0, h1;
; #pragma unroll
;                 for (int j = 0; j < 4; ++j) { h0[j] = fsilu(acc[ai][0][m][0][j] * r) * (acc[ai][1][m][0][j] * r); h1[j] = fsilu(acc[ai][0][m][1][j] * r) * (acc[ai][1][m][1][j] * r); }
;                 *(u32x4*)(O + (size_t)row * FF + colh) = pack8(h0, h1);
;             }
	v_exp_f32_e32 v190, v190
	v_exp_f32_e32 v191, v191
	v_exp_f32_e32 v192, v192
	v_exp_f32_e32 v193, v193
	v_pk_fma_f32 v[186:187], v[186:187], v[154:155], v[154:155] op_sel_hi:[1,0,0]
	v_pk_fma_f32 v[188:189], v[188:189], v[154:155], v[154:155] op_sel_hi:[1,0,0]
	v_pk_fma_f32 v[190:191], v[190:191], v[154:155], v[154:155] op_sel_hi:[1,0,0]
	v_pk_fma_f32 v[192:193], v[192:193], v[154:155], v[154:155] op_sel_hi:[1,0,0]
	v_rcp_f32_e32 v186, v186
	v_rcp_f32_e32 v187, v187
	v_rcp_f32_e32 v188, v188
	v_rcp_f32_e32 v189, v189
	v_rcp_f32_e32 v190, v190
	v_rcp_f32_e32 v191, v191
	v_rcp_f32_e32 v192, v192
	v_rcp_f32_e32 v193, v193
	v_pk_mul_f32 v[54:55], v[54:55], v[186:187]
	v_pk_mul_f32 v[56:57], v[56:57], v[188:189]
	v_pk_mul_f32 v[50:51], v[50:51], v[190:191]
	v_pk_mul_f32 v[52:53], v[52:53], v[192:193]
	v_cvt_pk_bf16_f32 v78, v54, v55
	v_cvt_pk_bf16_f32 v79, v56, v57
	v_cvt_pk_bf16_f32 v80, v50, v51
	v_cvt_pk_bf16_f32 v81, v52, v53
	v_add_u32_e32 v148, 0x58000, v147
	global_store_dwordx4 v148, v[78:81], s[6:7] sc1
	v_pk_mul_f32 v[186:187], v[38:39], v[172:173] op_sel_hi:[1,0]
	v_pk_mul_f32 v[188:189], v[40:41], v[172:173] op_sel_hi:[1,0]
	v_pk_mul_f32 v[190:191], v[26:27], v[172:173] op_sel_hi:[1,0]
	v_pk_mul_f32 v[192:193], v[28:29], v[172:173] op_sel_hi:[1,0]
	v_exp_f32_e32 v186, v186
	v_exp_f32_e32 v187, v187
	v_exp_f32_e32 v188, v188
	v_exp_f32_e32 v189, v189
	v_exp_f32_e32 v190, v190
	v_exp_f32_e32 v191, v191
	v_exp_f32_e32 v192, v192
	v_exp_f32_e32 v193, v193
	v_pk_fma_f32 v[186:187], v[186:187], v[156:157], v[156:157] op_sel_hi:[1,0,0]
	v_pk_fma_f32 v[188:189], v[188:189], v[156:157], v[156:157] op_sel_hi:[1,0,0]
	v_pk_fma_f32 v[190:191], v[190:191], v[156:157], v[156:157] op_sel_hi:[1,0,0]
	v_pk_fma_f32 v[192:193], v[192:193], v[156:157], v[156:157] op_sel_hi:[1,0,0]
	v_rcp_f32_e32 v186, v186
	v_rcp_f32_e32 v187, v187
	v_rcp_f32_e32 v188, v188
	v_rcp_f32_e32 v189, v189
	v_rcp_f32_e32 v190, v190
	v_rcp_f32_e32 v191, v191
	v_rcp_f32_e32 v192, v192
	v_rcp_f32_e32 v193, v193
	v_pk_mul_f32 v[22:23], v[22:23], v[186:187]
	v_pk_mul_f32 v[24:25], v[24:25], v[188:189]
	v_pk_mul_f32 v[18:19], v[18:19], v[190:191]
	v_pk_mul_f32 v[20:21], v[20:21], v[192:193]
	v_cvt_pk_bf16_f32 v38, v22, v23
	v_cvt_pk_bf16_f32 v39, v24, v25
	v_cvt_pk_bf16_f32 v40, v18, v19
	v_cvt_pk_bf16_f32 v41, v20, v21
	v_add_u32_e32 v148, 0x84000, v147
	global_store_dwordx4 v148, v[38:41], s[6:7] sc1
	v_pk_mul_f32 v[186:187], v[86:87], v[174:175] op_sel_hi:[1,0]
	v_pk_mul_f32 v[188:189], v[88:89], v[174:175] op_sel_hi:[1,0]
	v_pk_mul_f32 v[190:191], v[82:83], v[174:175] op_sel_hi:[1,0]
	v_pk_mul_f32 v[192:193], v[84:85], v[174:175] op_sel_hi:[1,0]
	v_exp_f32_e32 v186, v186
	v_exp_f32_e32 v187, v187
	v_exp_f32_e32 v188, v188
	v_exp_f32_e32 v189, v189
	v_exp_f32_e32 v190, v190
	v_exp_f32_e32 v191, v191
	v_exp_f32_e32 v192, v192
	v_exp_f32_e32 v193, v193
	v_pk_fma_f32 v[186:187], v[186:187], v[158:159], v[158:159] op_sel_hi:[1,0,0]
	v_pk_fma_f32 v[188:189], v[188:189], v[158:159], v[158:159] op_sel_hi:[1,0,0]
	v_pk_fma_f32 v[190:191], v[190:191], v[158:159], v[158:159] op_sel_hi:[1,0,0]
	v_pk_fma_f32 v[192:193], v[192:193], v[158:159], v[158:159] op_sel_hi:[1,0,0]
	v_rcp_f32_e32 v186, v186
	v_rcp_f32_e32 v187, v187
	v_rcp_f32_e32 v188, v188
	v_rcp_f32_e32 v189, v189
	v_rcp_f32_e32 v190, v190
	v_rcp_f32_e32 v191, v191
	v_rcp_f32_e32 v192, v192
	v_rcp_f32_e32 v193, v193
	v_pk_mul_f32 v[102:103], v[102:103], v[186:187]
	v_pk_mul_f32 v[104:105], v[104:105], v[188:189]
	v_pk_mul_f32 v[98:99], v[98:99], v[190:191]
	v_pk_mul_f32 v[100:101], v[100:101], v[192:193]
	v_cvt_pk_bf16_f32 v86, v102, v103
	v_cvt_pk_bf16_f32 v87, v104, v105
	v_cvt_pk_bf16_f32 v88, v98, v99
	v_cvt_pk_bf16_f32 v89, v100, v101
	v_add_u32_e32 v148, 0x160000, v147
	global_store_dwordx4 v148, v[86:89], s[6:7] sc1
	v_pk_mul_f32 v[186:187], v[62:63], v[176:177] op_sel_hi:[1,0]
	v_pk_mul_f32 v[188:189], v[64:65], v[176:177] op_sel_hi:[1,0]
	v_pk_mul_f32 v[190:191], v[58:59], v[176:177] op_sel_hi:[1,0]
	v_pk_mul_f32 v[192:193], v[60:61], v[176:177] op_sel_hi:[1,0]
	v_exp_f32_e32 v186, v186
	v_exp_f32_e32 v187, v187
	v_exp_f32_e32 v188, v188
	v_exp_f32_e32 v189, v189
	v_exp_f32_e32 v190, v190
	v_exp_f32_e32 v191, v191
	v_exp_f32_e32 v192, v192
	v_exp_f32_e32 v193, v193
	v_pk_fma_f32 v[186:187], v[186:187], v[160:161], v[160:161] op_sel_hi:[1,0,0]
; __device__ __forceinline__ float fsilu(float x) { return x * fsigmoid(x); }
; __device__ __forceinline__ u32x4 pack8(const f32x4 a, const f32x4 b) { u32x4 w; w.x = cvt_pk_bf16(a[0], a[1]); w.y = cvt_pk_bf16(a[2], a[3]); w.z = cvt_pk_bf16(b[0], b[1]); w.w = cvt_pk_bf16(b[2], b[3]); return w; }
;     __device__ __forceinline__ void operator()(const Acc& acc, const Unit& u, int wr, int wc, int fr, int fq) const {
;         int row0 = u.pm * BM + wr * 64 + fr, colh = u.pn * 128 + wc * 32 + 8 * fq; asm volatile("" : "+v"(row0), "+v"(colh));
;         float sq[2][4];
; #pragma unroll
;         for (int ai = 0; ai < 2; ++ai)
; #pragma unroll
;             for (int m = 0; m < 4; ++m) sq[ai][m] = ssq[row0 + ai * HALF + m * 16];
;     ...
;                 const float r = rsqrtf(sq[ai][m] * (1.0f / D) + EPS);
;                 f32x4 h0, h1;
; #pragma unroll
;                 for (int j = 0; j < 4; ++j) { h0[j] = fsilu(acc[ai][0][m][0][j] * r) * (acc[ai][1][m][0][j] * r); h1[j] = fsilu(acc[ai][0][m][1][j] * r) * (acc[ai][1][m][1][j] * r); }
;                 *(u32x4*)(O + (size_t)row * FF + colh) = pack8(h0, h1);
;             }
	v_pk_fma_f32 v[188:189], v[188:189], v[160:161], v[160:161] op_sel_hi:[1,0,0]
	v_pk_fma_f32 v[190:191], v[190:191], v[160:161], v[160:161] op_sel_hi:[1,0,0]
	v_pk_fma_f32 v[192:193], v[192:193], v[160:161], v[160:161] op_sel_hi:[1,0,0]
	v_rcp_f32_e32 v186, v186
	v_rcp_f32_e32 v187, v187
	v_rcp_f32_e32 v188, v188
	v_rcp_f32_e32 v189, v189
	v_rcp_f32_e32 v190, v190
	v_rcp_f32_e32 v191, v191
	v_rcp_f32_e32 v192, v192
	v_rcp_f32_e32 v193, v193
	v_pk_mul_f32 v[74:75], v[74:75], v[186:187]
	v_pk_mul_f32 v[76:77], v[76:77], v[188:189]
	v_pk_mul_f32 v[70:71], v[70:71], v[190:191]
	v_pk_mul_f32 v[72:73], v[72:73], v[192:193]
	v_cvt_pk_bf16_f32 v62, v74, v75
	v_cvt_pk_bf16_f32 v63, v76, v77
	v_cvt_pk_bf16_f32 v64, v70, v71
	v_cvt_pk_bf16_f32 v65, v72, v73
	v_add_u32_e32 v148, 0x18c000, v147
	global_store_dwordx4 v148, v[62:65], s[6:7] sc1
	v_pk_mul_f32 v[186:187], v[34:35], v[178:179] op_sel_hi:[1,0]
	v_pk_mul_f32 v[188:189], v[36:37], v[178:179] op_sel_hi:[1,0]
	v_pk_mul_f32 v[190:191], v[30:31], v[178:179] op_sel_hi:[1,0]
	v_pk_mul_f32 v[192:193], v[32:33], v[178:179] op_sel_hi:[1,0]
	v_exp_f32_e32 v186, v186
	v_exp_f32_e32 v187, v187
	v_exp_f32_e32 v188, v188
	v_exp_f32_e32 v189, v189
	v_exp_f32_e32 v190, v190
	v_exp_f32_e32 v191, v191
	v_exp_f32_e32 v192, v192
	v_exp_f32_e32 v193, v193
	v_pk_fma_f32 v[186:187], v[186:187], v[162:163], v[162:163] op_sel_hi:[1,0,0]
	v_pk_fma_f32 v[188:189], v[188:189], v[162:163], v[162:163] op_sel_hi:[1,0,0]
	v_pk_fma_f32 v[190:191], v[190:191], v[162:163], v[162:163] op_sel_hi:[1,0,0]
	v_pk_fma_f32 v[192:193], v[192:193], v[162:163], v[162:163] op_sel_hi:[1,0,0]
	v_rcp_f32_e32 v186, v186
	v_rcp_f32_e32 v187, v187
	v_rcp_f32_e32 v188, v188
	v_rcp_f32_e32 v189, v189
	v_rcp_f32_e32 v190, v190
	v_rcp_f32_e32 v191, v191
	v_rcp_f32_e32 v192, v192
	v_rcp_f32_e32 v193, v193
	v_pk_mul_f32 v[46:47], v[46:47], v[186:187]
	v_pk_mul_f32 v[48:49], v[48:49], v[188:189]
	v_pk_mul_f32 v[42:43], v[42:43], v[190:191]
	v_pk_mul_f32 v[44:45], v[44:45], v[192:193]
	v_cvt_pk_bf16_f32 v34, v46, v47
	v_cvt_pk_bf16_f32 v35, v48, v49
	v_cvt_pk_bf16_f32 v36, v42, v43
	v_cvt_pk_bf16_f32 v37, v44, v45
	v_add_u32_e32 v148, 0x1b8000, v147
	global_store_dwordx4 v148, v[34:37], s[6:7] sc1
	v_pk_mul_f32 v[186:187], v[6:7], v[184:185] op_sel_hi:[1,0]
	v_pk_mul_f32 v[188:189], v[8:9], v[184:185] op_sel_hi:[1,0]
	v_pk_mul_f32 v[190:191], v[2:3], v[184:185] op_sel_hi:[1,0]
	v_pk_mul_f32 v[192:193], v[4:5], v[184:185] op_sel_hi:[1,0]
	v_exp_f32_e32 v186, v186
	v_exp_f32_e32 v187, v187
	v_exp_f32_e32 v188, v188
	v_exp_f32_e32 v189, v189
	v_exp_f32_e32 v190, v190
	v_exp_f32_e32 v191, v191
	v_exp_f32_e32 v192, v192
	v_exp_f32_e32 v193, v193
	v_pk_fma_f32 v[186:187], v[186:187], v[164:165], v[164:165] op_sel_hi:[1,0,0]
	v_pk_fma_f32 v[188:189], v[188:189], v[164:165], v[164:165] op_sel_hi:[1,0,0]
	v_pk_fma_f32 v[190:191], v[190:191], v[164:165], v[164:165] op_sel_hi:[1,0,0]
	v_pk_fma_f32 v[192:193], v[192:193], v[164:165], v[164:165] op_sel_hi:[1,0,0]
	v_rcp_f32_e32 v186, v186
	v_rcp_f32_e32 v187, v187
	v_rcp_f32_e32 v188, v188
	v_rcp_f32_e32 v189, v189
	v_rcp_f32_e32 v190, v190
	v_rcp_f32_e32 v191, v191
	v_rcp_f32_e32 v192, v192
	v_rcp_f32_e32 v193, v193
	v_pk_mul_f32 v[14:15], v[14:15], v[186:187]
	v_pk_mul_f32 v[16:17], v[16:17], v[188:189]
	v_pk_mul_f32 v[10:11], v[10:11], v[190:191]
	v_pk_mul_f32 v[12:13], v[12:13], v[192:193]
	v_cvt_pk_bf16_f32 v6, v14, v15
	v_cvt_pk_bf16_f32 v7, v16, v17
	v_cvt_pk_bf16_f32 v8, v10, v11
	v_cvt_pk_bf16_f32 v9, v12, v13
	v_add_u32_e32 v148, 0x1e4000, v147
	global_store_dwordx4 v148, v[6:9], s[6:7] sc1
	s_and_b64 vcc, exec, s[16:17]
	s_cbranch_vccz .Lnopf_P1
	v_lshl_add_u32 v224, s14, 8, v136
	v_lshlrev_b32_e32 v224, 2, v224
	global_load_dword v216, v224, s[88:89]
	global_load_dword v217, v224, s[88:89] offset:64
	global_load_dword v218, v224, s[88:89] offset:128
	global_load_dword v219, v224, s[88:89] offset:192
	global_load_dword v220, v224, s[88:89] offset:512
	global_load_dword v221, v224, s[88:89] offset:576
	global_load_dword v222, v224, s[88:89] offset:640
	global_load_dword v223, v224, s[88:89] offset:704
.Lnopf_P1:
	s_andn2_b64 vcc, exec, s[16:17]
	s_mov_b64 s[6:7], -1
	s_cbranch_vccnz .LBB0_160
	s_andn2_b64 vcc, exec, s[4:5]
	s_cbranch_vccnz .LBB0_159
	s_barrier
	s_branch .LBB0_159

; #define PG8_STAGE(bufoff, gbase, voff) do { _Pragma("unroll") for (int _i = 0; _i < 2; ++_i) \
;         asm volatile("s_mov_b32 m0, %0\n\ts_nop 0\n\tglobal_load_lds_dwordx4 %1, %2" :: "s"(ldsb + (unsigned)(bufoff) + ldsw + (unsigned)(_i * 8192)), "v"((voff)[_i]), "s"((const char*)(gbase)) : "memory", "m0"); } while (0)
; #define PG8_WAIT_V(n) asm volatile("s_waitcnt vmcnt(" #n ")" ::: "memory")
; #define PG8_BAR __builtin_amdgcn_s_barrier()
; template <class Epi, class Sched>
; __device__ __forceinline__ void gemm_phase(LAS unsigned char* lds, const Gemm g, const Sched& S, const Epi& E) {
;     ...
;     PG8_STAGE(PG8_SB(0, 0), cB, voffB); PG8_STAGE(PG8_SB(0, 1), cB + hstepB, voffB); PG8_STAGE(PG8_SA(0, 0), cA, voffA); PG8_STAGE(PG8_SA(0, 1), cA + hstepA, voffA);
;     if (wr == 1) PG8_BAR;
;     PG8_WAIT_V(2); PG8_BAR;
;     PG8_STAGE(PG8_SB(1, 0), cB + kstep, voffB); PG8_STAGE(PG8_SA(1, 0), cA + kstep, voffA); PG8_STAGE(PG8_SB(1, 1), cB + hstepB + kstep, voffB);
;     PG8_WAIT_V(6); PG8_BAR;
;     __device__ __forceinline__ void operator()(const Acc& acc, const Unit& u, int wr, int wc, int fr, int fq) const {
;         int row0 = u.pm * BM + wr * 64 + fr, colh = u.pn * 128 + wc * 32 + 8 * fq; asm volatile("" : "+v"(row0), "+v"(colh));
;         float sq[2][4];
; #pragma unroll
;         for (int ai = 0; ai < 2; ++ai)
; #pragma unroll
;             for (int m = 0; m < 4; ++m) sq[ai][m] = ssq[row0 + ai * HALF + m * 16];
.LBB0_988:
	v_and_b32_e32 v2, 24, v2
	v_and_b32_e32 v3, 15, v0
	v_lshlrev_b32_e32 v4, 1, v2
	v_lshlrev_b32_e32 v5, 2, v0
	v_lshl_or_b32 v135, s1, 6, v3
	v_lshl_or_b32 v3, v3, 6, v4
	s_lshl_b32 s1, s1, 13
	v_and_b32_e32 v5, 32, v5
	v_bitop3_b32 v136, v3, s1, v5 bitop3:0xde
	s_lshl_b32 s1, s10, 5
	s_and_b32 s12, s1, 0x60
	v_lshlrev_b32_e32 v3, 6, v0
	s_movk_i32 s1, 0x3c0
	v_and_or_b32 v3, v3, s1, v4
	s_lshl_b32 s1, s12, 7
	s_add_i32 s53, s35, 0x18000
	s_sext_i32_i16 s7, s0
	s_add_u32 s0, s36, 0x80
	v_bitop3_b32 v137, s1, v3, v5 bitop3:0xf6
	s_waitcnt vmcnt(2)
	s_barrier
	s_addc_u32 s1, s37, 0
	s_mov_b32 m0, s53
	s_nop 0
	global_load_lds_dwordx4 v132, s[0:1]
	s_add_i32 s54, s35, 0x1a000
	s_add_i32 s55, s35, 0x8000
	s_mov_b32 m0, s54
	s_nop 0
	global_load_lds_dwordx4 v134, s[0:1]
	s_add_u32 s0, s30, 0x80
	s_addc_u32 s1, s31, 0
	s_mov_b32 m0, s55
	s_nop 0
	global_load_lds_dwordx4 v1, s[0:1]
	s_add_i32 s56, s35, 0xa000
	s_add_i32 s57, s35, 0x1c000
	s_mov_b32 m0, s56
	s_nop 0
	global_load_lds_dwordx4 v133, s[0:1]
	s_add_u32 s0, s36, 0x80080
	s_addc_u32 s1, s37, 0
	s_mov_b32 m0, s57
	s_nop 0
	global_load_lds_dwordx4 v132, s[0:1]
	s_add_i32 s58, s35, 0x1e000
	s_mov_b32 m0, s58
	s_nop 0
	global_load_lds_dwordx4 v134, s[0:1]
	s_waitcnt vmcnt(6)
	s_add_i32 s59, s35, 0xc000
	s_cmpk_lt_u32 s4, 0x100
	v_cmp_gt_u32_e64 s[0:1], 64, v0
	s_cselect_b64 s[10:11], -1, 0
	s_add_i32 s60, s35, 0xe000
	v_or_b32_e32 v138, s12, v2
	v_mov_b64_e32 v[130:131], 0x57f
	v_mov_b32_e32 v139, 0
	v_mov_b32_e32 v140, 0x358637bd
	s_mov_b32 s61, 0x800000
	s_movk_i32 s62, 0x2c00
	s_mov_b32 s63, 0
	s_barrier
	v_lshl_add_u32 v224, s6, 8, v135
	v_lshlrev_b32_e32 v224, 2, v224
	global_load_dword v216, v224, s[18:19]
	global_load_dword v217, v224, s[18:19] offset:64
	global_load_dword v218, v224, s[18:19] offset:128
	global_load_dword v219, v224, s[18:19] offset:192
	global_load_dword v220, v224, s[18:19] offset:512
	global_load_dword v221, v224, s[18:19] offset:576
	global_load_dword v222, v224, s[18:19] offset:640
	global_load_dword v223, v224, s[18:19] offset:704
	s_branch .LBB0_991

; __device__ __forceinline__ float fsilu(float x) { return x * fsigmoid(x); }
; __device__ __forceinline__ u32x4 pack8(const f32x4 a, const f32x4 b) { u32x4 w; w.x = cvt_pk_bf16(a[0], a[1]); w.y = cvt_pk_bf16(a[2], a[3]); w.z = cvt_pk_bf16(b[0], b[1]); w.w = cvt_pk_bf16(b[2], b[3]); return w; }
;     __device__ __forceinline__ void operator()(const Acc& acc, const Unit& u, int wr, int wc, int fr, int fq) const {
;         int row0 = u.pm * BM + wr * 64 + fr, colh = u.pn * 128 + wc * 32 + 8 * fq; asm volatile("" : "+v"(row0), "+v"(colh));
;         float sq[2][4];
; #pragma unroll
;         for (int ai = 0; ai < 2; ++ai)
; #pragma unroll
;             for (int m = 0; m < 4; ++m) sq[ai][m] = ssq[row0 + ai * HALF + m * 16];
;         asm volatile("" ::: "memory");
; #pragma unroll
;         for (int ai = 0; ai < 2; ++ai)
; #pragma unroll
;             for (int m = 0; m < 4; ++m) {
;                 const int row = row0 + ai * HALF + m * 16;
;                 const float r = rsqrtf(sq[ai][m] * (1.0f / D) + EPS);
;                 f32x4 h0, h1;
; #pragma unroll
;                 for (int j = 0; j < 4; ++j) { h0[j] = fsilu(acc[ai][0][m][0][j] * r) * (acc[ai][1][m][0][j] * r); h1[j] = fsilu(acc[ai][0][m][1][j] * r) * (acc[ai][1][m][1][j] * r); }
;                 *(u32x4*)(O + (size_t)row * FF + colh) = pack8(h0, h1);
;             }
.LBB0_1030:
	v_lshl_add_u32 v142, s6, 8, v135
	v_lshl_or_b32 v143, s7, 7, v138
	v_lshlrev_b32_e32 v144, 2, v142
	s_cmp_lg_u32 s6, 32
	s_cbranch_scc1 .Lhave_S_P7
	global_load_dword v216, v144, s[18:19]
	global_load_dword v217, v144, s[18:19] offset:64
	global_load_dword v218, v144, s[18:19] offset:128
	global_load_dword v219, v144, s[18:19] offset:192
	global_load_dword v220, v144, s[18:19] offset:512
	global_load_dword v221, v144, s[18:19] offset:576
	global_load_dword v222, v144, s[18:19] offset:640
	global_load_dword v223, v144, s[18:19] offset:704
	s_waitcnt vmcnt(0)
.Lhave_S_P7:
	v_readlane_b32 s6, v254, 40
	v_readlane_b32 s7, v254, 41
	v_mul_u32_u24_e32 v145, 0x2c00, v142
	v_lshl_add_u32 v145, v143, 1, v145
	v_pk_mul_f32 v[126:127], v[122:123], v[126:127]
	v_pk_mul_f32 v[128:129], v[124:125], v[128:129]
	v_pk_mul_f32 v[118:119], v[114:115], v[118:119]
	v_pk_mul_f32 v[120:121], v[116:117], v[120:121]
	v_pk_mul_f32 v[70:71], v[94:95], v[70:71]
	v_pk_mul_f32 v[72:73], v[96:97], v[72:73]
	v_pk_mul_f32 v[66:67], v[86:87], v[66:67]
	v_pk_mul_f32 v[68:69], v[88:89], v[68:69]
	v_pk_mul_f32 v[38:39], v[54:55], v[38:39]
	v_pk_mul_f32 v[40:41], v[56:57], v[40:41]
	v_pk_mul_f32 v[34:35], v[50:51], v[34:35]
	v_pk_mul_f32 v[36:37], v[52:53], v[36:37]
	v_pk_mul_f32 v[6:7], v[14:15], v[6:7]
	v_pk_mul_f32 v[8:9], v[16:17], v[8:9]
	v_pk_mul_f32 v[2:3], v[10:11], v[2:3]
	v_pk_mul_f32 v[4:5], v[12:13], v[4:5]
	v_pk_mul_f32 v[110:111], v[102:103], v[110:111]
	v_pk_mul_f32 v[112:113], v[104:105], v[112:113]
	v_pk_mul_f32 v[106:107], v[98:99], v[106:107]
	v_pk_mul_f32 v[108:109], v[100:101], v[108:109]
	v_pk_mul_f32 v[90:91], v[78:79], v[90:91]
	v_pk_mul_f32 v[92:93], v[80:81], v[92:93]
	v_pk_mul_f32 v[82:83], v[74:75], v[82:83]
	v_pk_mul_f32 v[84:85], v[76:77], v[84:85]
	v_pk_mul_f32 v[62:63], v[46:47], v[62:63]
	v_pk_mul_f32 v[64:65], v[48:49], v[64:65]
	v_pk_mul_f32 v[58:59], v[42:43], v[58:59]
	v_pk_mul_f32 v[60:61], v[44:45], v[60:61]
	v_pk_mul_f32 v[30:31], v[22:23], v[30:31]
	v_pk_mul_f32 v[32:33], v[24:25], v[32:33]
	v_pk_mul_f32 v[26:27], v[18:19], v[26:27]
	v_pk_mul_f32 v[28:29], v[20:21], v[28:29]
	v_fmamk_f32 v148, v216, 0x3a000000, v140
	v_fmamk_f32 v150, v217, 0x3a000000, v140
	v_fmamk_f32 v152, v218, 0x3a000000, v140
	v_fmamk_f32 v154, v219, 0x3a000000, v140
	v_fmamk_f32 v156, v220, 0x3a000000, v140
	v_fmamk_f32 v158, v221, 0x3a000000, v140
	v_fmamk_f32 v160, v222, 0x3a000000, v140
	v_fmamk_f32 v162, v223, 0x3a000000, v140
	v_rsq_f32_e32 v164, v148
	v_rsq_f32_e32 v166, v150
	v_rsq_f32_e32 v168, v152
	v_rsq_f32_e32 v170, v154
	v_rsq_f32_e32 v172, v156
	v_rsq_f32_e32 v174, v158
	v_rsq_f32_e32 v176, v160
	v_rsq_f32_e32 v178, v162
	v_mul_f32_e32 v164, 0xbfb8aa3b, v164
	v_mul_f32_e32 v166, 0xbfb8aa3b, v166
	v_mul_f32_e32 v168, 0xbfb8aa3b, v168
	v_mul_f32_e32 v170, 0xbfb8aa3b, v170
	v_mul_f32_e32 v172, 0xbfb8aa3b, v172
	v_mul_f32_e32 v174, 0xbfb8aa3b, v174
	v_mul_f32_e32 v176, 0xbfb8aa3b, v176
	v_mul_f32_e32 v178, 0xbfb8aa3b, v178
	v_pk_mul_f32 v[180:181], v[122:123], v[164:165] op_sel_hi:[1,0]
	v_pk_mul_f32 v[182:183], v[124:125], v[164:165] op_sel_hi:[1,0]
	v_pk_mul_f32 v[184:185], v[114:115], v[164:165] op_sel_hi:[1,0]
	v_pk_mul_f32 v[186:187], v[116:117], v[164:165] op_sel_hi:[1,0]
	v_exp_f32_e32 v180, v180
	v_exp_f32_e32 v181, v181
	v_exp_f32_e32 v182, v182
	v_exp_f32_e32 v183, v183
	v_exp_f32_e32 v184, v184
	v_exp_f32_e32 v185, v185
	v_exp_f32_e32 v186, v186
	v_exp_f32_e32 v187, v187
	v_pk_fma_f32 v[180:181], v[180:181], v[148:149], v[148:149] op_sel_hi:[1,0,0]
	v_pk_fma_f32 v[182:183], v[182:183], v[148:149], v[148:149] op_sel_hi:[1,0,0]
	v_pk_fma_f32 v[184:185], v[184:185], v[148:149], v[148:149] op_sel_hi:[1,0,0]
	v_pk_fma_f32 v[186:187], v[186:187], v[148:149], v[148:149] op_sel_hi:[1,0,0]
	v_rcp_f32_e32 v180, v180
	v_rcp_f32_e32 v181, v181
	v_rcp_f32_e32 v182, v182
	v_rcp_f32_e32 v183, v183
	v_rcp_f32_e32 v184, v184
	v_rcp_f32_e32 v185, v185
	v_rcp_f32_e32 v186, v186
	v_rcp_f32_e32 v187, v187
	v_pk_mul_f32 v[126:127], v[126:127], v[180:181]
	v_pk_mul_f32 v[128:129], v[128:129], v[182:183]
	v_pk_mul_f32 v[118:119], v[118:119], v[184:185]
	v_pk_mul_f32 v[120:121], v[120:121], v[186:187]
	v_cvt_pk_bf16_f32 v122, v126, v127
	v_cvt_pk_bf16_f32 v123, v128, v129
	v_cvt_pk_bf16_f32 v124, v118, v119
	v_cvt_pk_bf16_f32 v125, v120, v121
	global_store_dwordx4 v145, v[122:125], s[6:7] sc1
	v_pk_mul_f32 v[180:181], v[94:95], v[166:167] op_sel_hi:[1,0]
	v_pk_mul_f32 v[182:183], v[96:97], v[166:167] op_sel_hi:[1,0]
	v_pk_mul_f32 v[184:185], v[86:87], v[166:167] op_sel_hi:[1,0]
	v_pk_mul_f32 v[186:187], v[88:89], v[166:167] op_sel_hi:[1,0]
	v_exp_f32_e32 v180, v180
	v_exp_f32_e32 v181, v181
	v_exp_f32_e32 v182, v182
	v_exp_f32_e32 v183, v183
	v_exp_f32_e32 v184, v184
	v_exp_f32_e32 v185, v185
	v_exp_f32_e32 v186, v186
	v_exp_f32_e32 v187, v187
	v_pk_fma_f32 v[180:181], v[180:181], v[150:151], v[150:151] op_sel_hi:[1,0,0]
	v_pk_fma_f32 v[182:183], v[182:183], v[150:151], v[150:151] op_sel_hi:[1,0,0]
	v_pk_fma_f32 v[184:185], v[184:185], v[150:151], v[150:151] op_sel_hi:[1,0,0]
	v_pk_fma_f32 v[186:187], v[186:187], v[150:151], v[150:151] op_sel_hi:[1,0,0]
	v_rcp_f32_e32 v180, v180
	v_rcp_f32_e32 v181, v181
	v_rcp_f32_e32 v182, v182
	v_rcp_f32_e32 v183, v183
	v_rcp_f32_e32 v184, v184
	v_rcp_f32_e32 v185, v185
	v_rcp_f32_e32 v186, v186
	v_rcp_f32_e32 v187, v187
	v_pk_mul_f32 v[70:71], v[70:71], v[180:181]
	v_pk_mul_f32 v[72:73], v[72:73], v[182:183]
	v_pk_mul_f32 v[66:67], v[66:67], v[184:185]
	v_pk_mul_f32 v[68:69], v[68:69], v[186:187]
	v_cvt_pk_bf16_f32 v94, v70, v71
	v_cvt_pk_bf16_f32 v95, v72, v73
	v_cvt_pk_bf16_f32 v96, v66, v67
	v_cvt_pk_bf16_f32 v97, v68, v69
; __device__ __forceinline__ float fsilu(float x) { return x * fsigmoid(x); }
; __device__ __forceinline__ u32x4 pack8(const f32x4 a, const f32x4 b) { u32x4 w; w.x = cvt_pk_bf16(a[0], a[1]); w.y = cvt_pk_bf16(a[2], a[3]); w.z = cvt_pk_bf16(b[0], b[1]); w.w = cvt_pk_bf16(b[2], b[3]); return w; }
;     __device__ __forceinline__ void operator()(const Acc& acc, const Unit& u, int wr, int wc, int fr, int fq) const {
;     ...
;                 const float r = rsqrtf(sq[ai][m] * (1.0f / D) + EPS);
;                 f32x4 h0, h1;
; #pragma unroll
;                 for (int j = 0; j < 4; ++j) { h0[j] = fsilu(acc[ai][0][m][0][j] * r) * (acc[ai][1][m][0][j] * r); h1[j] = fsilu(acc[ai][0][m][1][j] * r) * (acc[ai][1][m][1][j] * r); }
;                 *(u32x4*)(O + (size_t)row * FF + colh) = pack8(h0, h1);
;             }
	v_add_u32_e32 v146, 0x2c000, v145
	global_store_dwordx4 v146, v[94:97], s[6:7] sc1
	v_pk_mul_f32 v[180:181], v[54:55], v[168:169] op_sel_hi:[1,0]
	v_pk_mul_f32 v[182:183], v[56:57], v[168:169] op_sel_hi:[1,0]
	v_pk_mul_f32 v[184:185], v[50:51], v[168:169] op_sel_hi:[1,0]
	v_pk_mul_f32 v[186:187], v[52:53], v[168:169] op_sel_hi:[1,0]
	v_exp_f32_e32 v180, v180
	v_exp_f32_e32 v181, v181
	v_exp_f32_e32 v182, v182
	v_exp_f32_e32 v183, v183
	v_exp_f32_e32 v184, v184
	v_exp_f32_e32 v185, v185
	v_exp_f32_e32 v186, v186
	v_exp_f32_e32 v187, v187
	v_pk_fma_f32 v[180:181], v[180:181], v[152:153], v[152:153] op_sel_hi:[1,0,0]
	v_pk_fma_f32 v[182:183], v[182:183], v[152:153], v[152:153] op_sel_hi:[1,0,0]
	v_pk_fma_f32 v[184:185], v[184:185], v[152:153], v[152:153] op_sel_hi:[1,0,0]
	v_pk_fma_f32 v[186:187], v[186:187], v[152:153], v[152:153] op_sel_hi:[1,0,0]
	v_rcp_f32_e32 v180, v180
	v_rcp_f32_e32 v181, v181
	v_rcp_f32_e32 v182, v182
	v_rcp_f32_e32 v183, v183
	v_rcp_f32_e32 v184, v184
	v_rcp_f32_e32 v185, v185
	v_rcp_f32_e32 v186, v186
	v_rcp_f32_e32 v187, v187
	v_pk_mul_f32 v[38:39], v[38:39], v[180:181]
	v_pk_mul_f32 v[40:41], v[40:41], v[182:183]
	v_pk_mul_f32 v[34:35], v[34:35], v[184:185]
	v_pk_mul_f32 v[36:37], v[36:37], v[186:187]
	v_cvt_pk_bf16_f32 v54, v38, v39
	v_cvt_pk_bf16_f32 v55, v40, v41
	v_cvt_pk_bf16_f32 v56, v34, v35
	v_cvt_pk_bf16_f32 v57, v36, v37
	v_add_u32_e32 v146, 0x58000, v145
	global_store_dwordx4 v146, v[54:57], s[6:7] sc1
	v_pk_mul_f32 v[180:181], v[14:15], v[170:171] op_sel_hi:[1,0]
	v_pk_mul_f32 v[182:183], v[16:17], v[170:171] op_sel_hi:[1,0]
	v_pk_mul_f32 v[184:185], v[10:11], v[170:171] op_sel_hi:[1,0]
	v_pk_mul_f32 v[186:187], v[12:13], v[170:171] op_sel_hi:[1,0]
	v_exp_f32_e32 v180, v180
	v_exp_f32_e32 v181, v181
	v_exp_f32_e32 v182, v182
	v_exp_f32_e32 v183, v183
	v_exp_f32_e32 v184, v184
	v_exp_f32_e32 v185, v185
	v_exp_f32_e32 v186, v186
	v_exp_f32_e32 v187, v187
	v_pk_fma_f32 v[180:181], v[180:181], v[154:155], v[154:155] op_sel_hi:[1,0,0]
	v_pk_fma_f32 v[182:183], v[182:183], v[154:155], v[154:155] op_sel_hi:[1,0,0]
	v_pk_fma_f32 v[184:185], v[184:185], v[154:155], v[154:155] op_sel_hi:[1,0,0]
	v_pk_fma_f32 v[186:187], v[186:187], v[154:155], v[154:155] op_sel_hi:[1,0,0]
	v_rcp_f32_e32 v180, v180
	v_rcp_f32_e32 v181, v181
	v_rcp_f32_e32 v182, v182
	v_rcp_f32_e32 v183, v183
	v_rcp_f32_e32 v184, v184
	v_rcp_f32_e32 v185, v185
	v_rcp_f32_e32 v186, v186
	v_rcp_f32_e32 v187, v187
	v_pk_mul_f32 v[6:7], v[6:7], v[180:181]
	v_pk_mul_f32 v[8:9], v[8:9], v[182:183]
	v_pk_mul_f32 v[2:3], v[2:3], v[184:185]
	v_pk_mul_f32 v[4:5], v[4:5], v[186:187]
	v_cvt_pk_bf16_f32 v14, v6, v7
	v_cvt_pk_bf16_f32 v15, v8, v9
	v_cvt_pk_bf16_f32 v16, v2, v3
	v_cvt_pk_bf16_f32 v17, v4, v5
	v_add_u32_e32 v146, 0x84000, v145
	global_store_dwordx4 v146, v[14:17], s[6:7] sc1
	v_pk_mul_f32 v[180:181], v[102:103], v[172:173] op_sel_hi:[1,0]
	v_pk_mul_f32 v[182:183], v[104:105], v[172:173] op_sel_hi:[1,0]
	v_pk_mul_f32 v[184:185], v[98:99], v[172:173] op_sel_hi:[1,0]
	v_pk_mul_f32 v[186:187], v[100:101], v[172:173] op_sel_hi:[1,0]
	v_exp_f32_e32 v180, v180
	v_exp_f32_e32 v181, v181
	v_exp_f32_e32 v182, v182
	v_exp_f32_e32 v183, v183
	v_exp_f32_e32 v184, v184
	v_exp_f32_e32 v185, v185
	v_exp_f32_e32 v186, v186
	v_exp_f32_e32 v187, v187
	v_pk_fma_f32 v[180:181], v[180:181], v[156:157], v[156:157] op_sel_hi:[1,0,0]
	v_pk_fma_f32 v[182:183], v[182:183], v[156:157], v[156:157] op_sel_hi:[1,0,0]
	v_pk_fma_f32 v[184:185], v[184:185], v[156:157], v[156:157] op_sel_hi:[1,0,0]
	v_pk_fma_f32 v[186:187], v[186:187], v[156:157], v[156:157] op_sel_hi:[1,0,0]
	v_rcp_f32_e32 v180, v180
	v_rcp_f32_e32 v181, v181
	v_rcp_f32_e32 v182, v182
	v_rcp_f32_e32 v183, v183
	v_rcp_f32_e32 v184, v184
	v_rcp_f32_e32 v185, v185
	v_rcp_f32_e32 v186, v186
	v_rcp_f32_e32 v187, v187
	v_pk_mul_f32 v[110:111], v[110:111], v[180:181]
	v_pk_mul_f32 v[112:113], v[112:113], v[182:183]
	v_pk_mul_f32 v[106:107], v[106:107], v[184:185]
	v_pk_mul_f32 v[108:109], v[108:109], v[186:187]
	v_cvt_pk_bf16_f32 v102, v110, v111
	v_cvt_pk_bf16_f32 v103, v112, v113
	v_cvt_pk_bf16_f32 v104, v106, v107
	v_cvt_pk_bf16_f32 v105, v108, v109
	v_add_u32_e32 v146, 0x160000, v145
	global_store_dwordx4 v146, v[102:105], s[6:7] sc1
	v_pk_mul_f32 v[180:181], v[78:79], v[174:175] op_sel_hi:[1,0]
	v_pk_mul_f32 v[182:183], v[80:81], v[174:175] op_sel_hi:[1,0]
	v_pk_mul_f32 v[184:185], v[74:75], v[174:175] op_sel_hi:[1,0]
	v_pk_mul_f32 v[186:187], v[76:77], v[174:175] op_sel_hi:[1,0]
	v_exp_f32_e32 v180, v180
	v_exp_f32_e32 v181, v181
	v_exp_f32_e32 v182, v182
; __device__ __forceinline__ float fsilu(float x) { return x * fsigmoid(x); }
; __device__ __forceinline__ u32x4 pack8(const f32x4 a, const f32x4 b) { u32x4 w; w.x = cvt_pk_bf16(a[0], a[1]); w.y = cvt_pk_bf16(a[2], a[3]); w.z = cvt_pk_bf16(b[0], b[1]); w.w = cvt_pk_bf16(b[2], b[3]); return w; }
;     __device__ __forceinline__ void operator()(const Acc& acc, const Unit& u, int wr, int wc, int fr, int fq) const {
;         int row0 = u.pm * BM + wr * 64 + fr, colh = u.pn * 128 + wc * 32 + 8 * fq; asm volatile("" : "+v"(row0), "+v"(colh));
;         float sq[2][4];
; #pragma unroll
;         for (int ai = 0; ai < 2; ++ai)
; #pragma unroll
;             for (int m = 0; m < 4; ++m) sq[ai][m] = ssq[row0 + ai * HALF + m * 16];
;     ...
;                 const float r = rsqrtf(sq[ai][m] * (1.0f / D) + EPS);
;                 f32x4 h0, h1;
; #pragma unroll
;                 for (int j = 0; j < 4; ++j) { h0[j] = fsilu(acc[ai][0][m][0][j] * r) * (acc[ai][1][m][0][j] * r); h1[j] = fsilu(acc[ai][0][m][1][j] * r) * (acc[ai][1][m][1][j] * r); }
;                 *(u32x4*)(O + (size_t)row * FF + colh) = pack8(h0, h1);
;             }
	v_exp_f32_e32 v183, v183
	v_exp_f32_e32 v184, v184
	v_exp_f32_e32 v185, v185
	v_exp_f32_e32 v186, v186
	v_exp_f32_e32 v187, v187
	v_pk_fma_f32 v[180:181], v[180:181], v[158:159], v[158:159] op_sel_hi:[1,0,0]
	v_pk_fma_f32 v[182:183], v[182:183], v[158:159], v[158:159] op_sel_hi:[1,0,0]
	v_pk_fma_f32 v[184:185], v[184:185], v[158:159], v[158:159] op_sel_hi:[1,0,0]
	v_pk_fma_f32 v[186:187], v[186:187], v[158:159], v[158:159] op_sel_hi:[1,0,0]
	v_rcp_f32_e32 v180, v180
	v_rcp_f32_e32 v181, v181
	v_rcp_f32_e32 v182, v182
	v_rcp_f32_e32 v183, v183
	v_rcp_f32_e32 v184, v184
	v_rcp_f32_e32 v185, v185
	v_rcp_f32_e32 v186, v186
	v_rcp_f32_e32 v187, v187
	v_pk_mul_f32 v[90:91], v[90:91], v[180:181]
	v_pk_mul_f32 v[92:93], v[92:93], v[182:183]
	v_pk_mul_f32 v[82:83], v[82:83], v[184:185]
	v_pk_mul_f32 v[84:85], v[84:85], v[186:187]
	v_cvt_pk_bf16_f32 v78, v90, v91
	v_cvt_pk_bf16_f32 v79, v92, v93
	v_cvt_pk_bf16_f32 v80, v82, v83
	v_cvt_pk_bf16_f32 v81, v84, v85
	v_add_u32_e32 v146, 0x18c000, v145
	global_store_dwordx4 v146, v[78:81], s[6:7] sc1
	v_pk_mul_f32 v[180:181], v[46:47], v[176:177] op_sel_hi:[1,0]
	v_pk_mul_f32 v[182:183], v[48:49], v[176:177] op_sel_hi:[1,0]
	v_pk_mul_f32 v[184:185], v[42:43], v[176:177] op_sel_hi:[1,0]
	v_pk_mul_f32 v[186:187], v[44:45], v[176:177] op_sel_hi:[1,0]
	v_exp_f32_e32 v180, v180
	v_exp_f32_e32 v181, v181
	v_exp_f32_e32 v182, v182
	v_exp_f32_e32 v183, v183
	v_exp_f32_e32 v184, v184
	v_exp_f32_e32 v185, v185
	v_exp_f32_e32 v186, v186
	v_exp_f32_e32 v187, v187
	v_pk_fma_f32 v[180:181], v[180:181], v[160:161], v[160:161] op_sel_hi:[1,0,0]
	v_pk_fma_f32 v[182:183], v[182:183], v[160:161], v[160:161] op_sel_hi:[1,0,0]
	v_pk_fma_f32 v[184:185], v[184:185], v[160:161], v[160:161] op_sel_hi:[1,0,0]
	v_pk_fma_f32 v[186:187], v[186:187], v[160:161], v[160:161] op_sel_hi:[1,0,0]
	v_rcp_f32_e32 v180, v180
	v_rcp_f32_e32 v181, v181
	v_rcp_f32_e32 v182, v182
	v_rcp_f32_e32 v183, v183
	v_rcp_f32_e32 v184, v184
	v_rcp_f32_e32 v185, v185
	v_rcp_f32_e32 v186, v186
	v_rcp_f32_e32 v187, v187
	v_pk_mul_f32 v[62:63], v[62:63], v[180:181]
	v_pk_mul_f32 v[64:65], v[64:65], v[182:183]
	v_pk_mul_f32 v[58:59], v[58:59], v[184:185]
	v_pk_mul_f32 v[60:61], v[60:61], v[186:187]
	v_cvt_pk_bf16_f32 v46, v62, v63
	v_cvt_pk_bf16_f32 v47, v64, v65
	v_cvt_pk_bf16_f32 v48, v58, v59
	v_cvt_pk_bf16_f32 v49, v60, v61
	v_add_u32_e32 v146, 0x1b8000, v145
	global_store_dwordx4 v146, v[46:49], s[6:7] sc1
	v_pk_mul_f32 v[180:181], v[22:23], v[178:179] op_sel_hi:[1,0]
	v_pk_mul_f32 v[182:183], v[24:25], v[178:179] op_sel_hi:[1,0]
	v_pk_mul_f32 v[184:185], v[18:19], v[178:179] op_sel_hi:[1,0]
	v_pk_mul_f32 v[186:187], v[20:21], v[178:179] op_sel_hi:[1,0]
	v_exp_f32_e32 v180, v180
	v_exp_f32_e32 v181, v181
	v_exp_f32_e32 v182, v182
	v_exp_f32_e32 v183, v183
	v_exp_f32_e32 v184, v184
	v_exp_f32_e32 v185, v185
	v_exp_f32_e32 v186, v186
	v_exp_f32_e32 v187, v187
	v_pk_fma_f32 v[180:181], v[180:181], v[162:163], v[162:163] op_sel_hi:[1,0,0]
	v_pk_fma_f32 v[182:183], v[182:183], v[162:163], v[162:163] op_sel_hi:[1,0,0]
	v_pk_fma_f32 v[184:185], v[184:185], v[162:163], v[162:163] op_sel_hi:[1,0,0]
	v_pk_fma_f32 v[186:187], v[186:187], v[162:163], v[162:163] op_sel_hi:[1,0,0]
	v_rcp_f32_e32 v180, v180
	v_rcp_f32_e32 v181, v181
	v_rcp_f32_e32 v182, v182
	v_rcp_f32_e32 v183, v183
	v_rcp_f32_e32 v184, v184
	v_rcp_f32_e32 v185, v185
	v_rcp_f32_e32 v186, v186
	v_rcp_f32_e32 v187, v187
	v_pk_mul_f32 v[30:31], v[30:31], v[180:181]
	v_pk_mul_f32 v[32:33], v[32:33], v[182:183]
	v_pk_mul_f32 v[26:27], v[26:27], v[184:185]
	v_pk_mul_f32 v[28:29], v[28:29], v[186:187]
	v_cvt_pk_bf16_f32 v22, v30, v31
	v_cvt_pk_bf16_f32 v23, v32, v33
	v_cvt_pk_bf16_f32 v24, v26, v27
	v_cvt_pk_bf16_f32 v25, v28, v29
	v_add_u32_e32 v146, 0x1e4000, v145
	global_store_dwordx4 v146, v[22:25], s[6:7] sc1
	s_and_b64 vcc, exec, s[22:23]
	s_cbranch_vccz .Lnopf_P7
	s_cmp_eq_u32 s20, 32
	s_cbranch_scc1 .Lnopf_P7
	v_lshl_add_u32 v224, s20, 8, v135
	v_lshlrev_b32_e32 v224, 2, v224
	global_load_dword v216, v224, s[18:19]
	global_load_dword v217, v224, s[18:19] offset:64
	global_load_dword v218, v224, s[18:19] offset:128
	global_load_dword v219, v224, s[18:19] offset:192
	global_load_dword v220, v224, s[18:19] offset:512
	global_load_dword v221, v224, s[18:19] offset:576
	global_load_dword v222, v224, s[18:19] offset:640
	global_load_dword v223, v224, s[18:19] offset:704
.Lnopf_P7:
	s_andn2_b64 vcc, exec, s[22:23]
	s_mov_b64 s[6:7], -1
	s_cbranch_vccnz .LBB0_990
	s_andn2_b64 vcc, exec, s[8:9]
	s_cbranch_vccnz .LBB0_989
	s_barrier
	s_branch .LBB0_989
